# early decode units on workgroups 176..255 only (80 units instead of 96)
# speedup vs baseline: 1.0207x; 1.0207x over previous
; #define LAS __attribute__((address_space(3)))
; __device__ __forceinline__ int fresh_lane() { int l; asm volatile("v_mbcnt_lo_u32_b32 %0, -1, 0\n\tv_mbcnt_hi_u32_b32 %0, -1, %0" : "=v"(l)); return l; }
; __device__ __forceinline__ unsigned xb_xcc_id() { return (unsigned)__builtin_amdgcn_s_getreg((3 << 11) | 20) & 0xFu; }
; __device__ __forceinline__ void phase_attention(const Params& P, const Ctx& C, int parts, int qset) {
;     unsigned* qc = (unsigned*)(P.ws + WS_CTL) + CW_QUEUE + qset * 512;
;     volatile LAS unsigned* slot = (volatile LAS unsigned*)(C.lds + MISC_OFF) + 16;
;     const bool fixed_ok = ((const float*)(P.ws + WS_PEB))[768] < 100.f;
;     const int x0 = (int)(xb_xcc_id() & 7u);
;     for (int i = 0; i < 8; ++i) { const int x = (x0 + i) & 7;
;         for (;;) {
;             __syncthreads();
;             if (C.wave == 0 && fresh_lane() == 0) *slot = __hip_atomic_fetch_add(qc + 64 * x, 1u, __ATOMIC_RELAXED, __HIP_MEMORY_SCOPE_AGENT);
;             __syncthreads();
;             const unsigned u = *slot;
;             if (u >= 128u) break;
;             const int us = __builtin_amdgcn_readfirstlane((int)u);
;             int pq = -1, dq = -1;
;             if (us < 96) { const int k = us / 3, r = us - 3 * k; if (r == 0) pq = 63 - k; else dq = 2 * k + r - 1; } else pq = 127 - us;
;             if (pq >= 0) { if (parts & 1) { if (fixed_ok) attn_prompt_unit<true>(P, C, x, pq); else attn_prompt_unit<false>(P, C, x, pq); } }
;             else { if (parts & 2) attn_decode_unit(P, C, x * 64 + dq); }
.LBB0_1136:
	s_bitcmp1_b32 s101, 1
	s_cbranch_scc1 .Lmy_e7
	s_bitset1_b32 s101, 1
	s_cmpk_lg_i32 s68, 0x100
	s_cbranch_scc1 .Lmy_e7
	s_bitset1_b32 s101, 3
	v_readlane_b32 s99, v254, 10
	s_cmpk_lt_u32 s99, 176
	s_cbranch_scc1 .Lmy_e7
	s_and_b32 s100, s99, 31
	s_mul_i32 s100, s100, 3
	s_add_i32 s100, s100, 1
	s_bitset1_b32 s101, 0
	s_waitcnt vmcnt(0)
	s_barrier
	s_mov_b64 s[2:3], -1
	s_branch .LBB0_1192

; __device__ __forceinline__ void phase_attention(const Params& P, const Ctx& C, int parts, int qset) {
;     ...
;             const unsigned u = *slot;
;             if (u >= 128u) break;
;             const int us = __builtin_amdgcn_readfirstlane((int)u);
;             int pq = -1, dq = -1;
;             if (us < 96) { const int k = us / 3, r = us - 3 * k; if (r == 0) pq = 63 - k; else dq = 2 * k + r - 1; } else pq = 127 - us;
;             if (pq >= 0) { if (parts & 1) { if (fixed_ok) attn_prompt_unit<true>(P, C, x, pq); else attn_prompt_unit<false>(P, C, x, pq); } }
;             else { if (parts & 2) attn_decode_unit(P, C, x * 64 + dq); }
.LBB0_1215:
	s_bitcmp1_b32 s101, 0
	s_cbranch_scc1 .Lmy_e8
	s_bitcmp1_b32 s101, 3
	s_cbranch_scc0 .Lmy_e8
	v_readlane_b32 s99, v254, 13
	s_add_i32 s99, s99, s4
	s_cmpk_lt_u32 s99, 352
	s_cbranch_scc1 .Lmy_e8
	s_bitcmp0_b32 s4, 0
	s_cbranch_scc1 .LBB0_1200
